# v38 with the SEAM3 leader's local-generation bump ordered before its cross-XCD arrival (formal ordering fix, same speed expected)
# speedup vs baseline: 1.0084x; 1.0084x over previous
; __device__ __forceinline__ unsigned xb_ld(unsigned* p)              { return __hip_atomic_load(p, __ATOMIC_RELAXED, __HIP_MEMORY_SCOPE_AGENT); }
; __device__ __forceinline__ unsigned xb_add(unsigned* p, unsigned v) { return __hip_atomic_fetch_add(p, v, __ATOMIC_RELAXED, __HIP_MEMORY_SCOPE_AGENT); }
; #define XB_SPIN(cond, bar) do { unsigned _sp = 0; while (cond) { __builtin_amdgcn_s_sleep(1); \
;     if ((++_sp & 255u) == 0u) { if (xb_ld(&(bar)[XB_TMO])) break; if (_sp > XB_SPIN_CAP) { atomicAdd(&(bar)[XB_TMO], 1u); break; } } } } while (0)
; __device__ __forceinline__ void xcd_barrier(const XcdBarrier& b) {
;     asm volatile("s_waitcnt vmcnt(0)" ::: "memory");
;     __syncthreads();
;     if (threadIdx.x == 0) {
;         unsigned* bar = b.bar;
;         __builtin_amdgcn_s_waitcnt(0);
;         unsigned nloc = b.st[0], nx = b.st[1];
;         if (nloc == 0u) { xcd_barrier_complete(bar, b.x, nloc, nx); b.st[0] = nloc; b.st[1] = nx; }
;         const unsigned old = xb_add(&bar[XB_XSUB(b.x)], 1u);
;         const unsigned gen = old / nloc;
;         if (old + 1u == (gen + 1u) * nloc) {
;             __builtin_amdgcn_fence(__ATOMIC_RELEASE, "agent");
;             asm volatile("s_waitcnt vmcnt(0)" ::: "memory");
;             const unsigned og = xb_add(&bar[XB_TOP], 1u);
;             const unsigned tg = og / nx;
;             if (og + 1u == (tg + 1u) * nx) xb_add(&bar[XB_TOPGEN], 1u);
;             else XB_SPIN(xb_ld(&bar[XB_TOPGEN]) == tg, bar);
;             __builtin_amdgcn_fence(__ATOMIC_ACQUIRE, "agent");
;             xb_add(&bar[XB_XGEN(b.x)], 1u);
;             asm volatile("s_waitcnt vmcnt(0)" ::: "memory");
.LBB0_350:
	s_cmp_gt_i32 s83, 4
	s_cselect_b64 s[0:1], -1, 0
	s_and_b64 s[4:5], s[4:5], s[0:1]
	s_andn2_b64 vcc, exec, s[4:5]
	s_cbranch_vccnz .LBB0_404
	s_waitcnt vmcnt(0) lgkmcnt(0)
	s_barrier
	s_mov_b64 s[4:5], exec
	v_readlane_b32 s6, v248, 2
	v_readlane_b32 s7, v248, 3
	s_and_b64 s[6:7], s[4:5], s[6:7]
	s_mov_b64 exec, s[6:7]
	s_cbranch_execz .Ls3_close
	s_add_i32 s6, 0, 0x27e00
	v_mov_b32_e32 v0, s6
	ds_read2_b32 v[2:3], v0 offset1:1
	v_readlane_b32 s10, v248, 0
	v_readlane_b32 s11, v248, 1
	s_lshl_b32 s6, s3, 8
	s_nop 1
	s_add_u32 s6, s10, s6
	s_addc_u32 s7, s11, 0
	v_mov_b32_e32 v4, 1
	v_mov_b32_e32 v5, 0x1000
	global_atomic_add v6, v5, v4, s[6:7] offset:1024 sc0
	s_waitcnt vmcnt(0) lgkmcnt(0)
	v_cvt_f32_u32_e32 v7, v2
	v_sub_u32_e32 v8, 0, v2
	v_rcp_iflag_f32_e32 v7, v7
	s_nop 0
	v_mul_f32_e32 v7, 0x4f7ffffe, v7
	v_cvt_u32_f32_e32 v7, v7
	v_mul_lo_u32 v8, v8, v7
	v_mul_hi_u32 v8, v7, v8
	v_add_u32_e32 v7, v7, v8
	v_mul_hi_u32 v7, v6, v7
	v_mul_lo_u32 v8, v7, v2
	v_sub_u32_e32 v8, v6, v8
	v_add_u32_e32 v9, 1, v7
	v_cmp_ge_u32_e32 vcc, v8, v2
	s_nop 1
	v_cndmask_b32_e32 v7, v7, v9, vcc
	v_sub_u32_e32 v9, v8, v2
	v_cndmask_b32_e32 v8, v8, v9, vcc
	v_add_u32_e32 v9, 1, v7
	v_cmp_ge_u32_e32 vcc, v8, v2
	s_nop 1
	v_cndmask_b32_e32 v7, v7, v9, vcc
	v_add_u32_e32 v9, 1, v7
	v_readfirstlane_b32 s98, v7
	v_mul_lo_u32 v9, v9, v2
	v_add_u32_e32 v10, 1, v6
	v_cmp_eq_u32_e32 vcc, v10, v9
	s_cbranch_vccz .Ls3_notleader
	buffer_wbl2 sc1
	s_waitcnt vmcnt(0)
	v_mov_b32_e32 v5, 0x2000
	global_atomic_add v5, v4, s[6:7] offset:1024
	v_mov_b32_e32 v5, 0x3000
	global_atomic_add v11, v5, v4, s[10:11] offset:1024 sc0
	v_add_u32_e32 v9, 1, v7
	v_mul_lo_u32 v9, v9, v3
	s_waitcnt vmcnt(0)
	v_add_u32_e32 v10, 1, v11
	v_cmp_eq_u32_e32 vcc, v10, v9
	s_cbranch_vccz .Ls3_notleader
	global_atomic_add v5, v4, s[10:11] offset:1280
